# adds: in-proj gates epilogue regenerated with v_permlane32_swap pairs so each lane issues 8 dwordx4 stores instead of 16 dwordx2 (same sigmoid instruction sequence)
# speedup vs baseline: 1.0672x; 1.0132x over previous
.LBB0_420:
	s_and_b64 vcc, exec, s[0:1]
	s_mov_b32 s72, 0x40000
	s_cbranch_vccz .LBB0_422
	v_add_u32_e32 v2, s83, v175
	s_waitcnt vmcnt(0)
	v_or_b32_e32 v132, v2, v174
	v_ashrrev_i32_e32 v133, 31, v132
	v_lshlrev_b64 v[134:135], 13, v[132:133]
	v_readlane_b32 s12, v253, 18
	s_lshl_b32 s42, s84, 7
	v_readlane_b32 s13, v253, 19
	s_lshl_b64 s[0:1], s[42:43], 1
	s_movk_i32 s2, 0xf000
	s_movk_i32 s4, 0xec00
	s_mov_b32 s5, -1
	s_movk_i32 s6, 0xec40
	s_mov_b32 s7, -1
	v_lshl_add_u64 v[134:135], s[12:13], 0, v[134:135]
	v_lshl_add_u64 v[136:137], v[134:135], 0, s[0:1]
	v_lshlrev_b32_e32 v2, 7, v173
	v_lshlrev_b32_e32 v134, 4, v172
	v_mov_b32_e32 v135, v3
	v_lshl_add_u64 v[136:137], v[136:137], 0, v[2:3]
	v_lshl_add_u64 v[136:137], v[136:137], 0, v[134:135]
	v_lshl_add_u64 v[136:137], v[136:137], 0, s[4:5]
	v_add_co_u32_e32 v138, vcc, 0x40000, v136
	s_nop 1
	v_addc_co_u32_e32 v139, vcc, 0, v137, vcc
	v_mul_f32_e32 v52, 0xbfb8aa3b, v52
	v_mul_f32_e32 v53, 0xbfb8aa3b, v53
	v_mul_f32_e32 v54, 0xbfb8aa3b, v54
	v_mul_f32_e32 v55, 0xbfb8aa3b, v55
	v_mul_f32_e32 v56, 0xbfb8aa3b, v56
	v_mul_f32_e32 v57, 0xbfb8aa3b, v57
	v_mul_f32_e32 v58, 0xbfb8aa3b, v58
	v_mul_f32_e32 v59, 0xbfb8aa3b, v59
	v_mul_f32_e32 v60, 0xbfb8aa3b, v60
	v_mul_f32_e32 v61, 0xbfb8aa3b, v61
	v_mul_f32_e32 v62, 0xbfb8aa3b, v62
	v_mul_f32_e32 v63, 0xbfb8aa3b, v63
	v_mul_f32_e32 v64, 0xbfb8aa3b, v64
	v_mul_f32_e32 v65, 0xbfb8aa3b, v65
	v_mul_f32_e32 v66, 0xbfb8aa3b, v66
	v_mul_f32_e32 v67, 0xbfb8aa3b, v67
	v_exp_f32_e32 v52, v52
	v_exp_f32_e32 v53, v53
	v_exp_f32_e32 v54, v54
	v_exp_f32_e32 v55, v55
	v_exp_f32_e32 v56, v56
	v_exp_f32_e32 v57, v57
	v_exp_f32_e32 v58, v58
	v_exp_f32_e32 v59, v59
	v_exp_f32_e32 v60, v60
	v_exp_f32_e32 v61, v61
	v_exp_f32_e32 v62, v62
	v_exp_f32_e32 v63, v63
	v_exp_f32_e32 v64, v64
	v_exp_f32_e32 v65, v65
	v_exp_f32_e32 v66, v66
	v_exp_f32_e32 v67, v67
	v_add_f32_e32 v52, 1.0, v52
	v_add_f32_e32 v53, 1.0, v53
	v_add_f32_e32 v54, 1.0, v54
	v_add_f32_e32 v55, 1.0, v55
	v_add_f32_e32 v56, 1.0, v56
	v_add_f32_e32 v57, 1.0, v57
	v_add_f32_e32 v58, 1.0, v58
	v_add_f32_e32 v59, 1.0, v59
	v_add_f32_e32 v60, 1.0, v60
	v_add_f32_e32 v61, 1.0, v61
	v_add_f32_e32 v62, 1.0, v62
	v_add_f32_e32 v63, 1.0, v63
	v_add_f32_e32 v64, 1.0, v64
	v_add_f32_e32 v65, 1.0, v65
	v_add_f32_e32 v66, 1.0, v66
	v_add_f32_e32 v67, 1.0, v67
	v_rcp_f32_e32 v52, v52
	v_rcp_f32_e32 v53, v53
	v_rcp_f32_e32 v54, v54
	v_rcp_f32_e32 v55, v55
	v_rcp_f32_e32 v56, v56
	v_rcp_f32_e32 v57, v57
	v_rcp_f32_e32 v58, v58
	v_rcp_f32_e32 v59, v59
	v_rcp_f32_e32 v60, v60
	v_rcp_f32_e32 v61, v61
	v_rcp_f32_e32 v62, v62
	v_rcp_f32_e32 v63, v63
	v_rcp_f32_e32 v64, v64
	v_rcp_f32_e32 v65, v65
	v_rcp_f32_e32 v66, v66
	v_rcp_f32_e32 v67, v67
	v_cvt_pk_bf16_f32 v52, v52, v53
	v_cvt_pk_bf16_f32 v53, v54, v55
	v_cvt_pk_bf16_f32 v54, v56, v57
	v_cvt_pk_bf16_f32 v55, v58, v59
	v_cvt_pk_bf16_f32 v56, v60, v61
	v_cvt_pk_bf16_f32 v57, v62, v63
	v_cvt_pk_bf16_f32 v58, v64, v65
	v_cvt_pk_bf16_f32 v59, v66, v67
	s_nop 1
	v_permlane32_swap_b32_e32 v52, v54
	v_permlane32_swap_b32_e32 v53, v55
	v_permlane32_swap_b32_e32 v56, v58
	v_permlane32_swap_b32_e32 v57, v59
	global_store_dwordx4 v[136:137], v[52:55], off
	global_store_dwordx4 v[136:137], v[56:59], off offset:32
	v_mul_f32_e32 v36, 0xbfb8aa3b, v36
	v_mul_f32_e32 v37, 0xbfb8aa3b, v37
	v_mul_f32_e32 v38, 0xbfb8aa3b, v38
	v_mul_f32_e32 v39, 0xbfb8aa3b, v39
	v_mul_f32_e32 v40, 0xbfb8aa3b, v40
	v_mul_f32_e32 v41, 0xbfb8aa3b, v41
	v_mul_f32_e32 v42, 0xbfb8aa3b, v42
	v_mul_f32_e32 v43, 0xbfb8aa3b, v43
	v_mul_f32_e32 v44, 0xbfb8aa3b, v44
	v_mul_f32_e32 v45, 0xbfb8aa3b, v45
	v_mul_f32_e32 v46, 0xbfb8aa3b, v46
	v_mul_f32_e32 v47, 0xbfb8aa3b, v47
	v_mul_f32_e32 v48, 0xbfb8aa3b, v48
	v_mul_f32_e32 v49, 0xbfb8aa3b, v49
	v_mul_f32_e32 v50, 0xbfb8aa3b, v50
	v_mul_f32_e32 v51, 0xbfb8aa3b, v51
	v_exp_f32_e32 v36, v36
	v_exp_f32_e32 v37, v37
	v_exp_f32_e32 v38, v38
	v_exp_f32_e32 v39, v39
	v_exp_f32_e32 v40, v40
	v_exp_f32_e32 v41, v41
	v_exp_f32_e32 v42, v42
	v_exp_f32_e32 v43, v43
	v_exp_f32_e32 v44, v44
	v_exp_f32_e32 v45, v45
	v_exp_f32_e32 v46, v46
	v_exp_f32_e32 v47, v47
	v_exp_f32_e32 v48, v48
	v_exp_f32_e32 v49, v49
	v_exp_f32_e32 v50, v50
	v_exp_f32_e32 v51, v51
	v_add_f32_e32 v36, 1.0, v36
	v_add_f32_e32 v37, 1.0, v37
	v_add_f32_e32 v38, 1.0, v38
	v_add_f32_e32 v39, 1.0, v39
	v_add_f32_e32 v40, 1.0, v40
	v_add_f32_e32 v41, 1.0, v41
	v_add_f32_e32 v42, 1.0, v42
	v_add_f32_e32 v43, 1.0, v43
	v_add_f32_e32 v44, 1.0, v44
	v_add_f32_e32 v45, 1.0, v45
	v_add_f32_e32 v46, 1.0, v46
	v_add_f32_e32 v47, 1.0, v47
	v_add_f32_e32 v48, 1.0, v48
	v_add_f32_e32 v49, 1.0, v49
	v_add_f32_e32 v50, 1.0, v50
	v_add_f32_e32 v51, 1.0, v51
	v_rcp_f32_e32 v36, v36
	v_rcp_f32_e32 v37, v37
	v_rcp_f32_e32 v38, v38
	v_rcp_f32_e32 v39, v39
	v_rcp_f32_e32 v40, v40
	v_rcp_f32_e32 v41, v41
	v_rcp_f32_e32 v42, v42
	v_rcp_f32_e32 v43, v43
	v_rcp_f32_e32 v44, v44
	v_rcp_f32_e32 v45, v45
	v_rcp_f32_e32 v46, v46
	v_rcp_f32_e32 v47, v47
	v_rcp_f32_e32 v48, v48
	v_rcp_f32_e32 v49, v49
	v_rcp_f32_e32 v50, v50
	v_rcp_f32_e32 v51, v51
	v_cvt_pk_bf16_f32 v36, v36, v37
	v_cvt_pk_bf16_f32 v37, v38, v39
	v_cvt_pk_bf16_f32 v38, v40, v41
	v_cvt_pk_bf16_f32 v39, v42, v43
	v_cvt_pk_bf16_f32 v40, v44, v45
	v_cvt_pk_bf16_f32 v41, v46, v47
	v_cvt_pk_bf16_f32 v42, v48, v49
	v_cvt_pk_bf16_f32 v43, v50, v51
	s_nop 1
	v_permlane32_swap_b32_e32 v36, v38
	v_permlane32_swap_b32_e32 v37, v39
	v_permlane32_swap_b32_e32 v40, v42
	v_permlane32_swap_b32_e32 v41, v43
	global_store_dwordx4 v[136:137], v[36:39], off offset:64
	global_store_dwordx4 v[136:137], v[40:43], off offset:96
	v_mul_f32_e32 v20, 0xbfb8aa3b, v20
	v_mul_f32_e32 v21, 0xbfb8aa3b, v21
	v_mul_f32_e32 v22, 0xbfb8aa3b, v22
	v_mul_f32_e32 v23, 0xbfb8aa3b, v23
	v_mul_f32_e32 v24, 0xbfb8aa3b, v24
	v_mul_f32_e32 v25, 0xbfb8aa3b, v25
	v_mul_f32_e32 v26, 0xbfb8aa3b, v26
	v_mul_f32_e32 v27, 0xbfb8aa3b, v27
	v_mul_f32_e32 v28, 0xbfb8aa3b, v28
	v_mul_f32_e32 v29, 0xbfb8aa3b, v29
	v_mul_f32_e32 v30, 0xbfb8aa3b, v30
	v_mul_f32_e32 v31, 0xbfb8aa3b, v31
	v_mul_f32_e32 v32, 0xbfb8aa3b, v32
	v_mul_f32_e32 v33, 0xbfb8aa3b, v33
	v_mul_f32_e32 v34, 0xbfb8aa3b, v34
	v_mul_f32_e32 v35, 0xbfb8aa3b, v35
	v_exp_f32_e32 v20, v20
	v_exp_f32_e32 v21, v21
	v_exp_f32_e32 v22, v22
	v_exp_f32_e32 v23, v23
	v_exp_f32_e32 v24, v24
	v_exp_f32_e32 v25, v25
	v_exp_f32_e32 v26, v26
	v_exp_f32_e32 v27, v27
	v_exp_f32_e32 v28, v28
	v_exp_f32_e32 v29, v29
	v_exp_f32_e32 v30, v30
	v_exp_f32_e32 v31, v31
	v_exp_f32_e32 v32, v32
	v_exp_f32_e32 v33, v33
	v_exp_f32_e32 v34, v34
	v_exp_f32_e32 v35, v35
	v_add_f32_e32 v20, 1.0, v20
	v_add_f32_e32 v21, 1.0, v21
	v_add_f32_e32 v22, 1.0, v22
	v_add_f32_e32 v23, 1.0, v23
	v_add_f32_e32 v24, 1.0, v24
	v_add_f32_e32 v25, 1.0, v25
	v_add_f32_e32 v26, 1.0, v26
	v_add_f32_e32 v27, 1.0, v27
	v_add_f32_e32 v28, 1.0, v28
	v_add_f32_e32 v29, 1.0, v29
	v_add_f32_e32 v30, 1.0, v30
	v_add_f32_e32 v31, 1.0, v31
	v_add_f32_e32 v32, 1.0, v32
	v_add_f32_e32 v33, 1.0, v33
	v_add_f32_e32 v34, 1.0, v34
	v_add_f32_e32 v35, 1.0, v35
	v_rcp_f32_e32 v20, v20
	v_rcp_f32_e32 v21, v21
	v_rcp_f32_e32 v22, v22
	v_rcp_f32_e32 v23, v23
	v_rcp_f32_e32 v24, v24
	v_rcp_f32_e32 v25, v25
	v_rcp_f32_e32 v26, v26
	v_rcp_f32_e32 v27, v27
	v_rcp_f32_e32 v28, v28
	v_rcp_f32_e32 v29, v29
	v_rcp_f32_e32 v30, v30
	v_rcp_f32_e32 v31, v31
	v_rcp_f32_e32 v32, v32
	v_rcp_f32_e32 v33, v33
	v_rcp_f32_e32 v34, v34
	v_rcp_f32_e32 v35, v35
	v_cvt_pk_bf16_f32 v20, v20, v21
	v_cvt_pk_bf16_f32 v21, v22, v23
	v_cvt_pk_bf16_f32 v22, v24, v25
	v_cvt_pk_bf16_f32 v23, v26, v27
	v_cvt_pk_bf16_f32 v24, v28, v29
	v_cvt_pk_bf16_f32 v25, v30, v31
	v_cvt_pk_bf16_f32 v26, v32, v33
	v_cvt_pk_bf16_f32 v27, v34, v35
	s_nop 1
	v_permlane32_swap_b32_e32 v20, v22
	v_permlane32_swap_b32_e32 v21, v23
	v_permlane32_swap_b32_e32 v24, v26
	v_permlane32_swap_b32_e32 v25, v27
	global_store_dwordx4 v[138:139], v[20:23], off
	global_store_dwordx4 v[138:139], v[24:27], off offset:32
	v_mul_f32_e32 v4, 0xbfb8aa3b, v4
	v_mul_f32_e32 v5, 0xbfb8aa3b, v5
	v_mul_f32_e32 v6, 0xbfb8aa3b, v6
	v_mul_f32_e32 v7, 0xbfb8aa3b, v7
	v_mul_f32_e32 v8, 0xbfb8aa3b, v8
	v_mul_f32_e32 v9, 0xbfb8aa3b, v9
	v_mul_f32_e32 v10, 0xbfb8aa3b, v10
	v_mul_f32_e32 v11, 0xbfb8aa3b, v11
	v_mul_f32_e32 v12, 0xbfb8aa3b, v12
	v_mul_f32_e32 v13, 0xbfb8aa3b, v13
	v_mul_f32_e32 v14, 0xbfb8aa3b, v14
	v_mul_f32_e32 v15, 0xbfb8aa3b, v15
	v_mul_f32_e32 v16, 0xbfb8aa3b, v16
	v_mul_f32_e32 v17, 0xbfb8aa3b, v17
	v_mul_f32_e32 v18, 0xbfb8aa3b, v18
	v_mul_f32_e32 v19, 0xbfb8aa3b, v19
	v_exp_f32_e32 v4, v4
	v_exp_f32_e32 v5, v5
	v_exp_f32_e32 v6, v6
	v_exp_f32_e32 v7, v7
	v_exp_f32_e32 v8, v8
	v_exp_f32_e32 v9, v9
	v_exp_f32_e32 v10, v10
	v_exp_f32_e32 v11, v11
	v_exp_f32_e32 v12, v12
	v_exp_f32_e32 v13, v13
	v_exp_f32_e32 v14, v14
	v_exp_f32_e32 v15, v15
	v_exp_f32_e32 v16, v16
	v_exp_f32_e32 v17, v17
	v_exp_f32_e32 v18, v18
	v_exp_f32_e32 v19, v19
	v_add_f32_e32 v4, 1.0, v4
	v_add_f32_e32 v5, 1.0, v5
	v_add_f32_e32 v6, 1.0, v6
	v_add_f32_e32 v7, 1.0, v7
	v_add_f32_e32 v8, 1.0, v8
	v_add_f32_e32 v9, 1.0, v9
	v_add_f32_e32 v10, 1.0, v10
	v_add_f32_e32 v11, 1.0, v11
	v_add_f32_e32 v12, 1.0, v12
	v_add_f32_e32 v13, 1.0, v13
	v_add_f32_e32 v14, 1.0, v14
	v_add_f32_e32 v15, 1.0, v15
	v_add_f32_e32 v16, 1.0, v16
	v_add_f32_e32 v17, 1.0, v17
	v_add_f32_e32 v18, 1.0, v18
	v_add_f32_e32 v19, 1.0, v19
	v_rcp_f32_e32 v4, v4
	v_rcp_f32_e32 v5, v5
	v_rcp_f32_e32 v6, v6
	v_rcp_f32_e32 v7, v7
	v_rcp_f32_e32 v8, v8
	v_rcp_f32_e32 v9, v9
	v_rcp_f32_e32 v10, v10
	v_rcp_f32_e32 v11, v11
	v_rcp_f32_e32 v12, v12
	v_rcp_f32_e32 v13, v13
	v_rcp_f32_e32 v14, v14
	v_rcp_f32_e32 v15, v15
	v_rcp_f32_e32 v16, v16
	v_rcp_f32_e32 v17, v17
	v_rcp_f32_e32 v18, v18
	v_rcp_f32_e32 v19, v19
	v_cvt_pk_bf16_f32 v4, v4, v5
	v_cvt_pk_bf16_f32 v5, v6, v7
	v_cvt_pk_bf16_f32 v6, v8, v9
	v_cvt_pk_bf16_f32 v7, v10, v11
	v_cvt_pk_bf16_f32 v8, v12, v13
	v_cvt_pk_bf16_f32 v9, v14, v15
	v_cvt_pk_bf16_f32 v10, v16, v17
	v_cvt_pk_bf16_f32 v11, v18, v19
	s_nop 1
	v_permlane32_swap_b32_e32 v4, v6
	v_permlane32_swap_b32_e32 v5, v7
	v_permlane32_swap_b32_e32 v8, v10
	v_permlane32_swap_b32_e32 v9, v11
	global_store_dwordx4 v[138:139], v[4:7], off offset:64
	global_store_dwordx4 v[138:139], v[8:11], off offset:96
	v_readlane_b32 s14, v253, 20
	v_readlane_b32 s15, v253, 21
	v_readlane_b32 s16, v253, 22
	v_readlane_b32 s17, v253, 23
	v_readlane_b32 s18, v253, 24
	v_readlane_b32 s19, v253, 25
